# prologue converts only layer-0 in-projection weights; the other f32-to-bf16 weight items run on idle workgroups of MIX2 and of the GEMM phases (static partition)
# speedup vs baseline: 1.0065x; 1.0056x over previous
.LBB0_1033:
	s_and_b64 vcc, exec, s[2:3]
	v_readlane_b32 s26, v254, 45
	v_readlane_b32 s27, v254, 46
	s_cbranch_vccz .LBB0_1094
	s_waitcnt vmcnt(0)
	s_mov_b32 s32, 0
	v_readlane_b32 s31, v251, 8
	s_movk_i32 s30, 0x2400
	s_cmp_lg_u32 s31, 0
	s_cselect_b32 s31, 0x7c0, s30
	s_mov_b32 s30, s6
	v_mov_b32_e32 v35, v178
	s_movk_i32 s2, 0x4100
	v_ashrrev_i32_e32 v47, 6, v35
	v_and_b32_e32 v34, 63, v35
	v_add_u32_e32 v46, s88, v47
	v_cmp_gt_i32_e32 vcc, s2, v46
	v_lshlrev_b32_e32 v36, 3, v34
	s_and_saveexec_b64 s[2:3], vcc
	s_cbranch_execz .LBB0_1047
	v_cmp_lt_i32_e32 vcc, v186, v250
	v_readlane_b32 s12, v254, 47
	v_mov_b32_e32 v37, v1
	v_cndmask_b32_e32 v0, v185, v186, vcc
	v_cmp_lt_i32_e32 vcc, v191, v250
	v_lshlrev_b32_e32 v48, 2, v0
	v_readlane_b32 s13, v254, 48
	v_cndmask_b32_e32 v0, v185, v191, vcc
	v_mov_b32_e32 v2, 0
	v_lshlrev_b32_e32 v49, 2, v0
	v_lshl_add_u64 v[38:39], s[12:13], 0, v[36:37]
	s_mov_b64 s[14:15], 0
	v_mov_b32_e32 v42, v46
	v_mov_b32_e32 v3, v2
	v_mov_b32_e32 v4, v2
	v_mov_b32_e32 v5, v2
	v_mov_b32_e32 v6, v2
	v_mov_b32_e32 v7, v2
	v_mov_b32_e32 v8, v2
	v_mov_b32_e32 v9, v2
	v_mov_b32_e32 v10, v2
	v_mov_b32_e32 v11, v2
	v_mov_b32_e32 v12, v2
	v_mov_b32_e32 v13, v2
	v_mov_b32_e32 v14, v2
	v_mov_b32_e32 v15, v2
	v_mov_b32_e32 v16, v2
	v_mov_b32_e32 v17, v2
	s_branch .LBB0_1037

.LBB0_1047:
	s_or_b64 exec, exec, s[2:3]
	v_cmp_gt_i32_e32 vcc, s31, v46
	s_and_saveexec_b64 s[2:3], vcc
	s_cbranch_execz .LBB0_1080
	s_movk_i32 s14, 0x4200
	v_mul_lo_u32 v0, v47, s14
	v_lshrrev_b32_e32 v14, 3, v34
	v_and_b32_e32 v2, 56, v36
	v_add_u32_e32 v0, 0, v0
	v_mul_u32_u24_e32 v4, 0x104, v2
	v_lshlrev_b32_e32 v5, 2, v14
	v_lshl_add_u32 v3, v34, 2, v0
	v_add3_u32 v15, v0, v4, v5
	v_or_b32_e32 v16, 8, v14
	v_or_b32_e32 v17, 16, v14
	v_or_b32_e32 v18, 24, v14
	v_or_b32_e32 v19, 32, v14
	v_or_b32_e32 v20, 40, v14
	v_or_b32_e32 v21, 48, v14
	v_or_b32_e32 v22, 56, v14
	v_lshlrev_b32_e32 v23, 6, v46
	s_lshl_b32 s26, s30, 6
	v_lshlrev_b32_e32 v24, 2, v46
	s_lshl_b32 s27, s30, 2
	s_mov_b64 s[14:15], 0
	s_branch .LBB0_1052

.LBB0_1051:
	s_or_b64 exec, exec, s[18:19]
	v_add_u32_e32 v46, s30, v46
	s_add_i32 s18, s31, -1
	v_cmp_lt_i32_e32 vcc, s18, v46
	v_add_u32_e32 v23, s26, v23
	s_or_b64 s[14:15], vcc, s[14:15]
	v_add_u32_e32 v24, s27, v24
	s_andn2_b64 exec, exec, s[14:15]
	s_cbranch_execz .LBB0_1080

.LBB0_1080:
	s_or_b64 exec, exec, s[2:3]
	s_cmp_lg_u32 s32, 0
	s_cbranch_scc1 .Lwt_ret
	v_readlane_b32 s2, v253, 53
	s_nop 1
	v_add_u32_e32 v2, s2, v35
	s_mov_b32 s2, 0x20000
	v_cmp_gt_i32_e32 vcc, s2, v2
	s_and_saveexec_b64 s[2:3], vcc
	v_readlane_b32 s14, v254, 22
	v_readlane_b32 s15, v254, 23
	v_readlane_b32 s18, v254, 24
	v_readlane_b32 s15, v254, 6
	v_readlane_b32 s19, v254, 25
	s_cbranch_execz .LBB0_1084
	v_readlane_b32 s12, v253, 57
	s_add_u32 s10, s12, s10
	v_readlane_b32 s12, v254, 2
	v_ashrrev_i32_e32 v3, 31, v2
	s_addc_u32 s11, s12, s11
	v_lshl_add_u64 v[4:5], v[2:3], 1, s[10:11]
	v_readlane_b32 s10, v254, 5
	s_nop 1
	v_lshl_add_u32 v3, v35, 6, s10
	s_mov_b64 s[10:11], 0

.Lsc_std:
	s_cmp_eq_u32 s48, 3
	s_cbranch_scc1 .Lsc_m2w
	s_cmp_eq_u32 s48, 1
	s_cbranch_scc1 .Lsc_g1
	s_cmp_eq_u32 s48, 5
	s_cbranch_scc1 .Lsc_g2
	s_cmp_eq_u32 s48, 6
	s_cbranch_scc1 .Lsc_g3
	s_cmp_eq_u32 s48, 8
	s_cbranch_scc1 .Lsc_g4
	s_cmp_eq_u32 s48, 9
	s_cbranch_scc1 .Lsc_g5
	s_branch .Lsc_done

.Lsc_loop:
	s_cmp_ge_u32 s51, s53
	s_cbranch_scc1 .Lsc_done
	s_add_i32 s60, s49, s51
	s_lshr_b32 s61, s60, 7
	s_lshl_b32 s61, s61, 22
	s_and_b32 s62, s60, 127
	s_lshl_b32 s62, s62, 15
	s_add_u32 s61, s61, s62
	s_add_u32 s62, s56, s61
	s_addc_u32 s63, s57, 0
	s_add_u32 s64, s58, s61
	s_addc_u32 s65, s59, 0
	global_load_dwordx4 v[8:11], v4, s[62:63] nt
	global_load_dwordx4 v[12:15], v4, s[62:63] offset:1024 nt
	global_load_dwordx4 v[16:19], v4, s[62:63] offset:2048 nt
	global_load_dwordx4 v[20:23], v4, s[62:63] offset:3072 nt
	global_load_dwordx4 v[24:27], v5, s[62:63] nt
	global_load_dwordx4 v[28:31], v5, s[62:63] offset:1024 nt
	global_load_dwordx4 v[32:35], v5, s[62:63] offset:2048 nt
	global_load_dwordx4 v[36:39], v5, s[62:63] offset:3072 nt
	global_load_dwordx4 v[40:43], v6, s[62:63] nt
	global_load_dwordx4 v[44:47], v6, s[62:63] offset:1024 nt
	global_load_dwordx4 v[48:51], v6, s[62:63] offset:2048 nt
	global_load_dwordx4 v[52:55], v6, s[62:63] offset:3072 nt
	global_load_dwordx4 v[56:59], v7, s[62:63] nt
	global_load_dwordx4 v[60:63], v7, s[62:63] offset:1024 nt
	global_load_dwordx4 v[64:67], v7, s[62:63] offset:2048 nt
	global_load_dwordx4 v[68:71], v7, s[62:63] offset:3072 nt
	s_waitcnt vmcnt(15)
	global_store_dwordx4 v4, v[8:11], s[64:65] nt
	s_waitcnt vmcnt(15)
	global_store_dwordx4 v4, v[12:15], s[64:65] offset:1024 nt
	s_waitcnt vmcnt(15)
	global_store_dwordx4 v4, v[16:19], s[64:65] offset:2048 nt
	s_waitcnt vmcnt(15)
	global_store_dwordx4 v4, v[20:23], s[64:65] offset:3072 nt
	s_waitcnt vmcnt(15)
	global_store_dwordx4 v5, v[24:27], s[64:65] nt
	s_waitcnt vmcnt(15)
	global_store_dwordx4 v5, v[28:31], s[64:65] offset:1024 nt
	s_waitcnt vmcnt(15)
	global_store_dwordx4 v5, v[32:35], s[64:65] offset:2048 nt
	s_waitcnt vmcnt(15)
	global_store_dwordx4 v5, v[36:39], s[64:65] offset:3072 nt
	s_waitcnt vmcnt(15)
	global_store_dwordx4 v6, v[40:43], s[64:65] nt
	s_waitcnt vmcnt(15)
	global_store_dwordx4 v6, v[44:47], s[64:65] offset:1024 nt
	s_waitcnt vmcnt(15)
	global_store_dwordx4 v6, v[48:51], s[64:65] offset:2048 nt
	s_waitcnt vmcnt(15)
	global_store_dwordx4 v6, v[52:55], s[64:65] offset:3072 nt
	s_waitcnt vmcnt(15)
	global_store_dwordx4 v7, v[56:59], s[64:65] nt
	s_waitcnt vmcnt(15)
	global_store_dwordx4 v7, v[60:63], s[64:65] offset:1024 nt
	s_waitcnt vmcnt(15)
	global_store_dwordx4 v7, v[64:67], s[64:65] offset:2048 nt
	s_waitcnt vmcnt(15)
	global_store_dwordx4 v7, v[68:71], s[64:65] offset:3072 nt
	s_add_i32 s51, s51, s52
	s_add_i32 s50, s50, -1
	s_cmp_lg_u32 s50, 0
	s_cbranch_scc1 .Lsc_loop
	s_branch .Lsc_done
.Lsc_wtg:
	s_lshr_b32 s55, s55, 1
	s_lshl_b32 s55, s55, 3
	s_add_i32 s55, s55, s46
	s_movk_i32 s30, 0x4000
	s_mul_i32 s67, s47, 0x1200
	s_cmp_eq_u32 s48, 5
	s_cbranch_scc0 .Lsc_wtg3
	s_add_i32 s64, s67, 0xc50
	s_add_i32 s31, s67, 0x1000
	s_branch .Lsc_wt_go
.Lsc_wtg3:
	s_cmp_eq_u32 s48, 6
	s_cbranch_scc0 .Lsc_wtg4
	s_movk_i32 s64, 0x1000
	s_movk_i32 s31, 0x13c0
	s_cmp_eq_u32 s47, 0
	s_cbranch_scc1 .Lsc_wt_go
	s_movk_i32 s64, 0x2200
	s_movk_i32 s31, 0x2400
	s_branch .Lsc_wt_go
.Lsc_wtg4:
	s_cmp_lg_u32 s47, 0
	s_cbranch_scc1 .Lsc_done
	s_movk_i32 s64, 0x13c0
	s_movk_i32 s31, 0x16c0
	s_cmp_eq_u32 s48, 8
	s_cbranch_scc1 .Lsc_wt_go
	s_cmp_eq_u32 s48, 9
	s_cbranch_scc0 .Lsc_done
	s_movk_i32 s64, 0x16c0
	s_movk_i32 s31, 0x19c0
	s_branch .Lsc_wt_go
.Lsc_m2w:
	s_mov_b32 s55, s45
	s_cmp_le_u32 s45, 32
	s_cbranch_scc1 .Lsc_m2w_go
	s_sub_i32 s55, s45, 192
	s_cmp_lt_u32 s45, 225
	s_cbranch_scc1 .Lsc_done
.Lsc_m2w_go:
	s_lshl_b32 s55, s55, 3
	s_add_i32 s55, s55, s46
	s_movk_i32 s30, 512
	s_mul_i32 s67, s47, 0x1200
	s_add_i32 s64, s67, 0x7c0
	s_add_i32 s31, s67, 0xc50
.Lsc_wt_go:
	s_add_i32 s64, s64, s55
	v_mov_b32_e32 v35, v178
	v_ashrrev_i32_e32 v47, 6, v35
	v_and_b32_e32 v34, 63, v35
	v_lshlrev_b32_e32 v36, 3, v34
	v_mov_b32_e32 v46, s64
	s_mov_b32 s32, 1
	s_mov_b64 s[2:3], exec
	s_branch .LBB0_1047
.Lwt_ret:
	s_mov_b32 s32, 0
